# c1 with the two channel-pair fma chains interleaved (no back-to-back dependent v_pk_fma)
# speedup vs baseline: 1.0044x; 1.0044x over previous
.LBB0_223:
	ds_read_b128 v[38:41], v2
	ds_read_b128 v[42:45], v2 offset:16
	ds_read_b64 v[4:5], v2 offset:32
	ds_read_b128 v[46:49], v2 offset:64
	ds_read_b128 v[50:53], v2 offset:80
	ds_read_b64 v[78:79], v2 offset:96
	ds_read_b128 v[54:57], v2 offset:128
	ds_read_b128 v[58:61], v2 offset:144
	ds_read_b64 v[174:175], v2 offset:160
	ds_read_b128 v[62:65], v2 offset:192
	ds_read_b128 v[66:69], v2 offset:208
	ds_read_b64 v[176:177], v2 offset:224
	ds_read_b128 v[70:73], v203
	ds_read_b128 v[74:77], v203 offset:16
	ds_read_b64 v[162:163], v203 offset:32
	ds_read_b128 v[80:83], v203 offset:64
	ds_read_b128 v[84:87], v203 offset:80
	ds_read_b64 v[168:169], v203 offset:96
	ds_read_b128 v[88:91], v203 offset:128
	ds_read_b128 v[92:95], v203 offset:144
	ds_read_b64 v[158:159], v203 offset:160
	ds_read_b128 v[96:99], v203 offset:192
	ds_read_b128 v[100:103], v203 offset:208
	ds_read_b64 v[160:161], v203 offset:224
	s_waitcnt vmcnt(4)
	s_waitcnt lgkmcnt(15)
	v_lshlrev_b32_e32 v252, 16, v14
	v_and_b32_e32 v253, 0xffff0000, v14
	v_lshlrev_b32_e32 v248, 16, v15
	v_and_b32_e32 v249, 0xffff0000, v15
	v_pk_fma_f32 v[4:5], v[38:39], v[252:253], v[4:5]
	v_pk_fma_f32 v[78:79], v[46:47], v[248:249], v[78:79]
	v_lshlrev_b32_e32 v254, 16, v18
	v_and_b32_e32 v255, 0xffff0000, v18
	v_lshlrev_b32_e32 v250, 16, v19
	v_and_b32_e32 v251, 0xffff0000, v19
	v_pk_fma_f32 v[4:5], v[40:41], v[254:255], v[4:5]
	v_pk_fma_f32 v[78:79], v[48:49], v[250:251], v[78:79]
	v_lshlrev_b32_e32 v252, 16, v22
	v_and_b32_e32 v253, 0xffff0000, v22
	v_lshlrev_b32_e32 v248, 16, v23
	v_and_b32_e32 v249, 0xffff0000, v23
	v_pk_fma_f32 v[4:5], v[42:43], v[252:253], v[4:5]
	v_pk_fma_f32 v[78:79], v[50:51], v[248:249], v[78:79]
	v_lshlrev_b32_e32 v254, 16, v34
	v_and_b32_e32 v255, 0xffff0000, v34
	v_lshlrev_b32_e32 v250, 16, v35
	v_and_b32_e32 v251, 0xffff0000, v35
	v_pk_fma_f32 v[4:5], v[44:45], v[254:255], v[4:5]
	v_pk_fma_f32 v[78:79], v[52:53], v[250:251], v[78:79]
	s_waitcnt lgkmcnt(12)
	v_lshlrev_b32_e32 v252, 16, v16
	v_and_b32_e32 v253, 0xffff0000, v16
	v_lshlrev_b32_e32 v248, 16, v17
	v_and_b32_e32 v249, 0xffff0000, v17
	v_pk_fma_f32 v[174:175], v[54:55], v[252:253], v[174:175]
	v_pk_fma_f32 v[176:177], v[62:63], v[248:249], v[176:177]
	v_lshlrev_b32_e32 v254, 16, v20
	v_and_b32_e32 v255, 0xffff0000, v20
	v_lshlrev_b32_e32 v250, 16, v21
	v_and_b32_e32 v251, 0xffff0000, v21
	v_pk_fma_f32 v[174:175], v[56:57], v[254:255], v[174:175]
	v_pk_fma_f32 v[176:177], v[64:65], v[250:251], v[176:177]
	v_lshlrev_b32_e32 v252, 16, v24
	v_and_b32_e32 v253, 0xffff0000, v24
	v_lshlrev_b32_e32 v248, 16, v25
	v_and_b32_e32 v249, 0xffff0000, v25
	v_pk_fma_f32 v[174:175], v[58:59], v[252:253], v[174:175]
	v_pk_fma_f32 v[176:177], v[66:67], v[248:249], v[176:177]
	v_lshlrev_b32_e32 v254, 16, v36
	v_and_b32_e32 v255, 0xffff0000, v36
	v_lshlrev_b32_e32 v250, 16, v37
	v_and_b32_e32 v251, 0xffff0000, v37
	v_pk_fma_f32 v[174:175], v[60:61], v[254:255], v[174:175]
	v_pk_fma_f32 v[176:177], v[68:69], v[250:251], v[176:177]
	ds_read_b128 v[46:49], v211 offset:24576
	ds_read_b128 v[38:41], v211 offset:16384
	ds_read_b128 v[50:53], v212 offset:16384
	ds_read_b128 v[54:57], v211 offset:16896
	ds_read_b128 v[62:65], v211 offset:25088
	ds_read_b128 v[66:69], v212 offset:16896
	s_waitcnt lgkmcnt(12)
	v_lshlrev_b32_e32 v252, 16, v10
	v_and_b32_e32 v253, 0xffff0000, v10
	v_lshlrev_b32_e32 v248, 16, v11
	v_and_b32_e32 v249, 0xffff0000, v11
	v_pk_fma_f32 v[162:163], v[70:71], v[252:253], v[162:163]
	v_pk_fma_f32 v[168:169], v[80:81], v[248:249], v[168:169]
	v_lshlrev_b32_e32 v254, 16, v6
	v_and_b32_e32 v255, 0xffff0000, v6
	v_lshlrev_b32_e32 v250, 16, v7
	v_and_b32_e32 v251, 0xffff0000, v7
	v_pk_fma_f32 v[162:163], v[72:73], v[254:255], v[162:163]
	v_pk_fma_f32 v[168:169], v[82:83], v[250:251], v[168:169]
	v_lshlrev_b32_e32 v252, 16, v26
	v_and_b32_e32 v253, 0xffff0000, v26
	v_lshlrev_b32_e32 v248, 16, v27
	v_and_b32_e32 v249, 0xffff0000, v27
	v_pk_fma_f32 v[162:163], v[74:75], v[252:253], v[162:163]
	v_pk_fma_f32 v[168:169], v[84:85], v[248:249], v[168:169]
	v_lshlrev_b32_e32 v254, 16, v30
	v_and_b32_e32 v255, 0xffff0000, v30
	v_lshlrev_b32_e32 v250, 16, v31
	v_and_b32_e32 v251, 0xffff0000, v31
	v_pk_fma_f32 v[162:163], v[76:77], v[254:255], v[162:163]
	v_pk_fma_f32 v[168:169], v[86:87], v[250:251], v[168:169]
	s_waitcnt lgkmcnt(6)
	v_lshlrev_b32_e32 v252, 16, v12
	v_and_b32_e32 v253, 0xffff0000, v12
	v_lshlrev_b32_e32 v248, 16, v13
	v_and_b32_e32 v249, 0xffff0000, v13
	v_pk_fma_f32 v[158:159], v[88:89], v[252:253], v[158:159]
	v_pk_fma_f32 v[160:161], v[96:97], v[248:249], v[160:161]
	v_lshlrev_b32_e32 v254, 16, v8
	v_and_b32_e32 v255, 0xffff0000, v8
	v_lshlrev_b32_e32 v250, 16, v9
	v_and_b32_e32 v251, 0xffff0000, v9
	v_pk_fma_f32 v[158:159], v[90:91], v[254:255], v[158:159]
	v_pk_fma_f32 v[160:161], v[98:99], v[250:251], v[160:161]
	v_lshlrev_b32_e32 v252, 16, v28
	v_and_b32_e32 v253, 0xffff0000, v28
	v_lshlrev_b32_e32 v248, 16, v29
	v_and_b32_e32 v249, 0xffff0000, v29
	v_pk_fma_f32 v[158:159], v[92:93], v[252:253], v[158:159]
	v_pk_fma_f32 v[160:161], v[100:101], v[248:249], v[160:161]
	v_lshlrev_b32_e32 v254, 16, v32
	v_and_b32_e32 v255, 0xffff0000, v32
	v_lshlrev_b32_e32 v250, 16, v33
	v_and_b32_e32 v251, 0xffff0000, v33
	v_pk_fma_f32 v[158:159], v[94:95], v[254:255], v[158:159]
	v_pk_fma_f32 v[160:161], v[102:103], v[250:251], v[160:161]
	s_cmpk_eq_i32 s2, 0x70
	s_cbranch_scc1 .Llru_noload
	v_add3_u32 v248, v113, s2, 13
	v_mul_u32_u24_e32 v248, 0x1200, v248
	v_lshl_add_u32 v248, v104, 1, v248
	v_add_u32_e32 v249, 0x1200, v248
	v_add_u32_e32 v250, 0x2400, v248
	v_add_u32_e32 v251, 0x3600, v248
	global_load_dwordx4 v[14:17], v248, s[88:89]
	global_load_dwordx4 v[10:13], v248, s[88:89] offset:64
	global_load_dwordx4 v[18:21], v249, s[88:89]
	global_load_dwordx4 v[6:9], v249, s[88:89] offset:64
	global_load_dwordx4 v[22:25], v250, s[88:89]
	global_load_dwordx4 v[26:29], v250, s[88:89] offset:64
	global_load_dwordx4 v[34:37], v251, s[88:89]
	global_load_dwordx4 v[30:33], v251, s[88:89] offset:64
